# adds: next-tile prefetch in the w_in_b (q|k|v|gate) transpose loop with masked partial tiles
# baseline (speedup 1.0000x reference)
; DI unsigned cvt_pk_bf16(float lo, float hi) { unsigned r; asm("v_cvt_pk_bf16_f32 %0, %1, %2" : "=v"(r) : "v"(lo), "v"(hi)); return r; }
; DI void conv_tile(float* tile, bf16_t* dst, int Kdim, const float* src, int ld, int n0, int k0, int sc0, int nvalid) {
;     const int tid = threadIdx.x;
; #pragma unroll
;     for (int it = 0; it < 2; ++it) {
;         const int idx = tid + 512 * it, kk = idx >> 4, c4 = (idx & 15) * 4;
;         f32x4 v = (f32x4){0.f, 0.f, 0.f, 0.f};
;         if (c4 < nvalid) v = *(const f32x4*)(src + (size_t)(k0 + kk) * ld + sc0 + c4);
;         float* tp = tile + kk * 65 + c4; tp[0] = v[0]; tp[1] = v[1]; tp[2] = v[2]; tp[3] = v[3];
;     }
;     __syncthreads();
;     { const int n = tid >> 3, k8 = (tid & 7) * 8; const float* tp = tile + k8 * 65 + n;
;       u32x4 w; w.x = cvt_pk_bf16(tp[0], tp[65]); w.y = cvt_pk_bf16(tp[130], tp[195]); w.z = cvt_pk_bf16(tp[260], tp[325]); w.w = cvt_pk_bf16(tp[390], tp[455]);
;       *(u32x4*)(dst + (size_t)(n0 + n) * Kdim + k0 + k8) = w; }
;     __syncthreads();
; __device__ void phase_convB1(const Params& p, unsigned char* shm) {
;     float* tile = (float*)shm; bf16_t* W = (bf16_t*)(p.ws + OFF_WINB);
;     for (int t = blockIdx.x; t < 100 * 32; t += gridDim.x) {
;         const int nblk = t >> 5, kb = t & 31, n0 = nblk * 64;
;         int sc0 = n0, nv = 64; if (n0 == 6144) { sc0 = 10240; nv = 32; } else if (n0 > 6144) { sc0 = 0; nv = 0; }
;         conv_tile(tile, W, 2048, p.in[8], 10272, n0, kb * 64, sc0, nv);
;     }
.LBB0_423:
	s_or_b64 exec, exec, s[6:7]
	v_lshlrev_b32_e32 v0, 2, v136
	v_add_u32_e32 v2, 0x200, v136
	v_and_b32_e32 v22, 60, v0
	v_lshrrev_b32_e32 v16, 4, v136
	v_lshrrev_b32_e32 v17, 4, v2
	v_lshrrev_b32_e32 v18, 3, v136
	v_and_b32_e32 v3, 56, v20
	v_lshl_add_u32 v0, v22, 2, 0
	v_mul_u32_u24_e32 v1, 0x104, v16
	v_mul_u32_u24_e32 v2, 0x104, v17
	v_mul_u32_u24_e32 v4, 0x104, v3
	v_lshlrev_b32_e32 v5, 2, v18
	s_cmpk_gt_i32 s2, 0xc7f
	s_mov_b32 s7, 0
	s_waitcnt lgkmcnt(0)
	v_mov_b32_e32 v13, 0
	v_add3_u32 v19, 0, v4, v5
	v_add_u32_e32 v20, v0, v1
	v_add_u32_e32 v21, v0, v2
	v_lshlrev_b32_e32 v8, 2, v22
	v_lshlrev_b32_e32 v10, 1, v3
	s_cbranch_scc1 .LBB0_428
	s_add_u32 s8, s26, 0x28000000
	v_mov_b32_e32 v9, v13
	s_addc_u32 s9, s27, 0
	v_lshl_add_u64 v[14:15], s[36:37], 0, v[8:9]
	s_lshl_b32 s0, s2, 6
	s_lshl_b32 s1, s30, 6
	s_lshl_b32 s3, s2, 1
	s_lshl_b32 s16, s30, 1
	v_mov_b32_e32 v11, v13
	v_add_u32_e32 v9, 0x400, v19
	s_mov_b32 s17, s2
	s_and_b32 s6, s3, 0xffffffc0
	s_cmpk_gt_i32 s6, 0x1800
	s_cselect_b64 s[12:13], -1, 0
	s_and_b64 s[10:11], s[12:13], exec
	s_cselect_b32 s18, 0, 64
	s_cmpk_eq_i32 s6, 0x1800
	s_cselect_b64 s[14:15], -1, 0
	s_and_b64 s[10:11], s[14:15], exec
	s_cselect_b32 s10, 32, s18
	s_and_b32 s18, s0, 0x7c0
	v_cmp_gt_u32_e32 vcc, s10, v22
	v_mov_b32_e32 v30, 0
	v_mov_b32_e32 v31, 0
	v_mov_b32_e32 v32, 0
	v_mov_b32_e32 v33, 0
	v_mov_b32_e32 v34, 0
	v_mov_b32_e32 v35, 0
	v_mov_b32_e32 v36, 0
	v_mov_b32_e32 v37, 0
	v_add_u32_e32 v38, s6, v18
	v_ashrrev_i32_e32 v39, 31, v38
	v_lshlrev_b64 v[38:39], 12, v[38:39]
	v_lshl_add_u64 v[38:39], s[8:9], 0, v[38:39]
	s_and_saveexec_b64 s[10:11], vcc
	s_cbranch_execz .Lcb1_skip_p
	s_and_b64 s[12:13], s[12:13], exec
	s_cselect_b32 s19, 0, s6
	s_and_b64 s[12:13], s[14:15], exec
	s_cselect_b32 s12, 0x2800, s19
	s_ashr_i32 s13, s12, 31
	v_or_b32_e32 v2, s18, v16
	v_lshl_add_u64 v[0:1], s[12:13], 2, v[14:15]
	v_mul_u32_u24_e32 v12, 0x2820, v2
	v_add_u32_e32 v2, s18, v17
	v_lshl_add_u64 v[24:25], v[12:13], 2, v[0:1]
	v_mul_u32_u24_e32 v12, 0x2820, v2
	v_lshl_add_u64 v[26:27], v[12:13], 2, v[0:1]
	global_load_dwordx4 v[34:37], v[24:25], off
	global_load_dwordx4 v[30:33], v[26:27], off
.Lcb1_skip_p:
	s_or_b64 exec, exec, s[10:11]
	s_lshl_b32 s6, s18, 1
	v_lshl_add_u64 v[38:39], v[38:39], 0, s[6:7]
	s_add_i32 s17, s17, s30
	s_add_i32 s0, s0, s1
	s_add_i32 s3, s3, s16
	v_lshl_add_u64 v[38:39], v[38:39], 0, v[10:11]
	s_cmpk_lt_i32 s17, 0xc80
	s_cselect_b64 s[98:99], -1, 0
	s_waitcnt vmcnt(0)
.Lcb1_loop:
	s_waitcnt vmcnt(1)
	ds_write2_b32 v20, v34, v35 offset1:1
	ds_write2_b32 v20, v36, v37 offset0:2 offset1:3
	ds_write2_b32 v21, v30, v31 offset1:1
	ds_write2_b32 v21, v32, v33 offset0:2 offset1:3
	s_waitcnt lgkmcnt(0)
	s_barrier
	v_mov_b64 v[40:41], v[38:39]
	s_mov_b64 s[100:101], s[98:99]
	s_and_b64 vcc, exec, s[98:99]
	s_cbranch_vccz .Lcb1_nonext
	s_and_b32 s6, s3, 0xffffffc0
	s_cmpk_gt_i32 s6, 0x1800
	s_cselect_b64 s[12:13], -1, 0
	s_and_b64 s[10:11], s[12:13], exec
	s_cselect_b32 s18, 0, 64
	s_cmpk_eq_i32 s6, 0x1800
	s_cselect_b64 s[14:15], -1, 0
	s_and_b64 s[10:11], s[14:15], exec
	s_cselect_b32 s10, 32, s18
	s_and_b32 s18, s0, 0x7c0
	v_cmp_gt_u32_e32 vcc, s10, v22
	v_mov_b32_e32 v30, 0
	v_mov_b32_e32 v31, 0
	v_mov_b32_e32 v32, 0
	v_mov_b32_e32 v33, 0
	v_mov_b32_e32 v34, 0
	v_mov_b32_e32 v35, 0
	v_mov_b32_e32 v36, 0
	v_mov_b32_e32 v37, 0
	v_add_u32_e32 v38, s6, v18
	v_ashrrev_i32_e32 v39, 31, v38
	v_lshlrev_b64 v[38:39], 12, v[38:39]
	v_lshl_add_u64 v[38:39], s[8:9], 0, v[38:39]
	s_and_saveexec_b64 s[10:11], vcc
	s_cbranch_execz .Lcb1_skip_l
	s_and_b64 s[12:13], s[12:13], exec
	s_cselect_b32 s19, 0, s6
	s_and_b64 s[12:13], s[14:15], exec
	s_cselect_b32 s12, 0x2800, s19
	s_ashr_i32 s13, s12, 31
	v_or_b32_e32 v2, s18, v16
	v_lshl_add_u64 v[0:1], s[12:13], 2, v[14:15]
	v_mul_u32_u24_e32 v12, 0x2820, v2
	v_add_u32_e32 v2, s18, v17
	v_lshl_add_u64 v[24:25], v[12:13], 2, v[0:1]
	v_mul_u32_u24_e32 v12, 0x2820, v2
	v_lshl_add_u64 v[26:27], v[12:13], 2, v[0:1]
	global_load_dwordx4 v[34:37], v[24:25], off
	global_load_dwordx4 v[30:33], v[26:27], off
.Lcb1_skip_l:
	s_or_b64 exec, exec, s[10:11]
	s_lshl_b32 s6, s18, 1
	v_lshl_add_u64 v[38:39], v[38:39], 0, s[6:7]
	s_add_i32 s17, s17, s30
	s_add_i32 s0, s0, s1
	s_add_i32 s3, s3, s16
	v_lshl_add_u64 v[38:39], v[38:39], 0, v[10:11]
	s_cmpk_lt_i32 s17, 0xc80
	s_cselect_b64 s[98:99], -1, 0
.Lcb1_nonext:
	ds_read2_b32 v[0:1], v19 offset1:65
	ds_read2_b32 v[2:3], v19 offset0:130 offset1:195
	ds_read2_b32 v[4:5], v9 offset0:4 offset1:69
	ds_read2_b32 v[6:7], v9 offset0:134 offset1:199
	s_waitcnt lgkmcnt(3)
	v_cvt_pk_bf16_f32 v0, v0, v1
	s_waitcnt lgkmcnt(2)
	v_cvt_pk_bf16_f32 v1, v2, v3
	s_waitcnt lgkmcnt(1)
	v_cvt_pk_bf16_f32 v2, v4, v5
	s_waitcnt lgkmcnt(0)
	v_cvt_pk_bf16_f32 v3, v6, v7
	global_store_dwordx4 v[40:41], v[0:3], off
	s_barrier
	s_and_b64 vcc, exec, s[100:101]
	s_cbranch_vccnz .Lcb1_loop
